# v24: v23 + EpiRes epilogue: first-half residual loads issued before the wave-half alignment barrier
# baseline (speedup 1.0000x reference)
.LBB0_137:
	s_add_i32 s68, s64, 2
	s_add_u32 s69, s62, 0x80
	s_addc_u32 s65, s63, 0
	s_add_i32 s72, 0, 0x10000
	s_cmp_eq_u32 s26, s64
	s_cselect_b32 s65, s49, s65
	s_cselect_b32 s64, s48, s69
	s_cselect_b32 s71, s61, s67
	s_cselect_b32 s70, s60, s41
	s_add_i32 s69, 0, 0x14000
	v_add_u32_e32 v142, s72, v187
	v_add_u32_e32 v168, s69, v187
	ds_read_b128 v[130:133], v142
	ds_read_b128 v[134:137], v142 offset:1024
	ds_read_b128 v[138:141], v142 offset:2048
	ds_read_b128 v[142:145], v142 offset:3072
	ds_read_b128 v[146:149], v168
	ds_read_b128 v[150:153], v168 offset:1024
	ds_read_b128 v[154:157], v168 offset:2048
	ds_read_b128 v[168:171], v168 offset:3072
	v_lshl_add_u64 v[184:185], s[62:63], 0, v[164:165]
	s_add_i32 m0, s5, 0xc000
	ds_read_b128 v[172:175], v189
	ds_read_b128 v[176:179], v189 offset:1024
	ds_read_b128 v[180:183], v189 offset:2048
	ds_read_b128 v[190:193], v189 offset:3072
	ds_read_b128 v[196:199], v189 offset:4096
	ds_read_b128 v[200:203], v189 offset:5120
	ds_read_b128 v[204:207], v189 offset:6144
	ds_read_b128 v[214:217], v189 offset:7168
	global_load_lds_dwordx4 v[184:185], off
	v_lshl_add_u64 v[184:185], s[62:63], 0, v[166:167]
	s_add_i32 m0, s5, 0xe000
	s_nop 0
	global_load_lds_dwordx4 v[184:185], off
	s_waitcnt vmcnt(8)
	s_waitcnt lgkmcnt(0)
	s_barrier
	s_setprio 1
	s_waitcnt lgkmcnt(0)
	v_mfma_f32_16x16x32_bf16 v[126:129], v[130:133], v[172:175], v[126:129]
	v_mfma_f32_16x16x32_bf16 v[122:125], v[138:141], v[172:175], v[122:125]
	v_mfma_f32_16x16x32_bf16 v[110:113], v[130:133], v[180:183], v[110:113]
	v_mfma_f32_16x16x32_bf16 v[106:109], v[138:141], v[180:183], v[106:109]
	v_mfma_f32_16x16x32_bf16 v[94:97], v[130:133], v[196:199], v[94:97]
	v_mfma_f32_16x16x32_bf16 v[90:93], v[138:141], v[196:199], v[90:93]
	v_mfma_f32_16x16x32_bf16 v[78:81], v[130:133], v[204:207], v[78:81]
	v_mfma_f32_16x16x32_bf16 v[74:77], v[138:141], v[204:207], v[74:77]
	v_mfma_f32_16x16x32_bf16 v[126:129], v[134:137], v[176:179], v[126:129]
	v_mfma_f32_16x16x32_bf16 v[122:125], v[142:145], v[176:179], v[122:125]
	v_mfma_f32_16x16x32_bf16 v[110:113], v[134:137], v[190:193], v[110:113]
	v_mfma_f32_16x16x32_bf16 v[106:109], v[142:145], v[190:193], v[106:109]
	v_mfma_f32_16x16x32_bf16 v[94:97], v[134:137], v[200:203], v[94:97]
	v_mfma_f32_16x16x32_bf16 v[90:93], v[142:145], v[200:203], v[90:93]
	v_mfma_f32_16x16x32_bf16 v[78:81], v[134:137], v[214:217], v[78:81]
	v_mfma_f32_16x16x32_bf16 v[74:77], v[142:145], v[214:217], v[74:77]
	s_setprio 0
	s_setprio 1
	v_mfma_f32_16x16x32_bf16 v[118:121], v[146:149], v[172:175], v[118:121]
	v_mfma_f32_16x16x32_bf16 v[114:117], v[154:157], v[172:175], v[114:117]
	v_mfma_f32_16x16x32_bf16 v[102:105], v[146:149], v[180:183], v[102:105]
	v_mfma_f32_16x16x32_bf16 v[98:101], v[154:157], v[180:183], v[98:101]
	v_mfma_f32_16x16x32_bf16 v[86:89], v[146:149], v[196:199], v[86:89]
	v_mfma_f32_16x16x32_bf16 v[82:85], v[154:157], v[196:199], v[82:85]
	v_mfma_f32_16x16x32_bf16 v[70:73], v[146:149], v[204:207], v[70:73]
	v_mfma_f32_16x16x32_bf16 v[66:69], v[154:157], v[204:207], v[66:69]
	v_mfma_f32_16x16x32_bf16 v[118:121], v[150:153], v[176:179], v[118:121]
	v_mfma_f32_16x16x32_bf16 v[114:117], v[168:171], v[176:179], v[114:117]
	v_mfma_f32_16x16x32_bf16 v[102:105], v[150:153], v[190:193], v[102:105]
	v_mfma_f32_16x16x32_bf16 v[98:101], v[168:171], v[190:193], v[98:101]
	v_mfma_f32_16x16x32_bf16 v[86:89], v[150:153], v[200:203], v[86:89]
	v_mfma_f32_16x16x32_bf16 v[82:85], v[168:171], v[200:203], v[82:85]
	v_mfma_f32_16x16x32_bf16 v[70:73], v[150:153], v[214:217], v[70:73]
	v_mfma_f32_16x16x32_bf16 v[66:69], v[168:171], v[214:217], v[66:69]
	s_setprio 0
	s_barrier
	s_add_i32 s72, s72, s4
	v_lshl_add_u64 v[184:185], s[70:71], 0, v[0:1]
	s_mov_b32 m0, s72
	ds_read_b128 v[172:175], v189 offset:16384
	ds_read_b128 v[176:179], v189 offset:17408
	ds_read_b128 v[180:183], v189 offset:18432
	ds_read_b128 v[190:193], v189 offset:19456
	ds_read_b128 v[196:199], v189 offset:20480
	ds_read_b128 v[200:203], v189 offset:21504
	ds_read_b128 v[204:207], v189 offset:22528
	ds_read_b128 v[214:217], v189 offset:23552
	global_load_lds_dwordx4 v[184:185], off
	s_add_i32 m0, s72, 0x2000
	v_lshl_add_u64 v[208:209], s[70:71], 0, v[158:159]
	s_add_u32 s70, s70, s30
	s_addc_u32 s71, s71, 0
	s_add_i32 s69, s69, s4
	global_load_lds_dwordx4 v[208:209], off
	v_lshl_add_u64 v[228:229], s[70:71], 0, v[0:1]
	s_mov_b32 m0, s69
	v_lshl_add_u64 v[230:231], s[70:71], 0, v[158:159]
	global_load_lds_dwordx4 v[228:229], off
	s_add_i32 m0, s69, 0x2000
	v_lshl_add_u64 v[232:233], s[64:65], 0, v[162:163]
	global_load_lds_dwordx4 v[230:231], off
	s_mov_b32 m0, s5
	v_lshl_add_u64 v[234:235], s[64:65], 0, v[160:161]
	global_load_lds_dwordx4 v[232:233], off
	s_mov_b32 m0, s9
	s_nop 0
	global_load_lds_dwordx4 v[234:235], off
	s_waitcnt vmcnt(8)
	s_waitcnt lgkmcnt(0)
	s_barrier
	s_setprio 1
	s_waitcnt lgkmcnt(0)
	v_mfma_f32_16x16x32_bf16 v[62:65], v[130:133], v[172:175], v[62:65]
	v_mfma_f32_16x16x32_bf16 v[58:61], v[138:141], v[172:175], v[58:61]
	v_mfma_f32_16x16x32_bf16 v[46:49], v[130:133], v[180:183], v[46:49]
	v_mfma_f32_16x16x32_bf16 v[42:45], v[138:141], v[180:183], v[42:45]
	v_mfma_f32_16x16x32_bf16 v[30:33], v[130:133], v[196:199], v[30:33]
	v_mfma_f32_16x16x32_bf16 v[26:29], v[138:141], v[196:199], v[26:29]
	v_mfma_f32_16x16x32_bf16 v[14:17], v[130:133], v[204:207], v[14:17]
	v_mfma_f32_16x16x32_bf16 v[10:13], v[138:141], v[204:207], v[10:13]
	v_mfma_f32_16x16x32_bf16 v[62:65], v[134:137], v[176:179], v[62:65]
	v_mfma_f32_16x16x32_bf16 v[58:61], v[142:145], v[176:179], v[58:61]
	v_mfma_f32_16x16x32_bf16 v[46:49], v[134:137], v[190:193], v[46:49]
	v_mfma_f32_16x16x32_bf16 v[42:45], v[142:145], v[190:193], v[42:45]
	v_mfma_f32_16x16x32_bf16 v[30:33], v[134:137], v[200:203], v[30:33]
	v_mfma_f32_16x16x32_bf16 v[26:29], v[142:145], v[200:203], v[26:29]
	v_mfma_f32_16x16x32_bf16 v[14:17], v[134:137], v[214:217], v[14:17]
	v_mfma_f32_16x16x32_bf16 v[10:13], v[142:145], v[214:217], v[10:13]
	s_setprio 0
	s_setprio 1
	v_mfma_f32_16x16x32_bf16 v[54:57], v[146:149], v[172:175], v[54:57]
	v_mfma_f32_16x16x32_bf16 v[50:53], v[154:157], v[172:175], v[50:53]
	v_mfma_f32_16x16x32_bf16 v[38:41], v[146:149], v[180:183], v[38:41]
	v_mfma_f32_16x16x32_bf16 v[34:37], v[154:157], v[180:183], v[34:37]
	v_mfma_f32_16x16x32_bf16 v[22:25], v[146:149], v[196:199], v[22:25]
	v_mfma_f32_16x16x32_bf16 v[18:21], v[154:157], v[196:199], v[18:21]
	v_mfma_f32_16x16x32_bf16 v[6:9], v[146:149], v[204:207], v[6:9]
	v_mfma_f32_16x16x32_bf16 v[2:5], v[154:157], v[204:207], v[2:5]
	v_mfma_f32_16x16x32_bf16 v[54:57], v[150:153], v[176:179], v[54:57]
	v_mfma_f32_16x16x32_bf16 v[50:53], v[168:171], v[176:179], v[50:53]
	v_mfma_f32_16x16x32_bf16 v[38:41], v[150:153], v[190:193], v[38:41]
	v_mfma_f32_16x16x32_bf16 v[34:37], v[168:171], v[190:193], v[34:37]
	v_mfma_f32_16x16x32_bf16 v[22:25], v[150:153], v[200:203], v[22:25]
	v_mfma_f32_16x16x32_bf16 v[18:21], v[168:171], v[200:203], v[18:21]
	v_mfma_f32_16x16x32_bf16 v[6:9], v[150:153], v[214:217], v[6:9]
	v_mfma_f32_16x16x32_bf16 v[2:5], v[168:171], v[214:217], v[2:5]
	s_setprio 0
	s_barrier
	s_add_i32 s69, 0, 0x1c000
	v_add_u32_e32 v142, s19, v187
	v_add_u32_e32 v168, s69, v187
	ds_read_b128 v[130:133], v142
	ds_read_b128 v[134:137], v142 offset:1024
	ds_read_b128 v[138:141], v142 offset:2048
	ds_read_b128 v[142:145], v142 offset:3072
	ds_read_b128 v[146:149], v168
	ds_read_b128 v[150:153], v168 offset:1024
	ds_read_b128 v[154:157], v168 offset:2048
	ds_read_b128 v[168:171], v168 offset:3072
	s_add_u32 s64, s64, s30
	s_addc_u32 s65, s65, 0
	s_mov_b32 m0, s10
	v_lshl_add_u64 v[236:237], s[64:65], 0, v[162:163]
	ds_read_b128 v[172:175], v189 offset:32768
	ds_read_b128 v[176:179], v189 offset:33792
	ds_read_b128 v[180:183], v189 offset:34816
	ds_read_b128 v[190:193], v189 offset:35840
	ds_read_b128 v[196:199], v189 offset:36864
	ds_read_b128 v[200:203], v189 offset:37888
	ds_read_b128 v[204:207], v189 offset:38912
	ds_read_b128 v[214:217], v189 offset:39936
	global_load_lds_dwordx4 v[236:237], off
	v_lshl_add_u64 v[236:237], s[64:65], 0, v[160:161]
	s_mov_b32 m0, s11
	s_nop 0
	global_load_lds_dwordx4 v[236:237], off
	s_waitcnt vmcnt(8)
	s_waitcnt lgkmcnt(0)
	s_barrier
	s_setprio 1
	s_waitcnt lgkmcnt(0)
	v_mfma_f32_16x16x32_bf16 v[126:129], v[130:133], v[172:175], v[126:129]
	v_mfma_f32_16x16x32_bf16 v[122:125], v[138:141], v[172:175], v[122:125]
	v_mfma_f32_16x16x32_bf16 v[110:113], v[130:133], v[180:183], v[110:113]
	v_mfma_f32_16x16x32_bf16 v[106:109], v[138:141], v[180:183], v[106:109]
	v_mfma_f32_16x16x32_bf16 v[94:97], v[130:133], v[196:199], v[94:97]
	v_mfma_f32_16x16x32_bf16 v[90:93], v[138:141], v[196:199], v[90:93]
	v_mfma_f32_16x16x32_bf16 v[78:81], v[130:133], v[204:207], v[78:81]
	v_mfma_f32_16x16x32_bf16 v[74:77], v[138:141], v[204:207], v[74:77]
	v_mfma_f32_16x16x32_bf16 v[126:129], v[134:137], v[176:179], v[126:129]
	v_mfma_f32_16x16x32_bf16 v[122:125], v[142:145], v[176:179], v[122:125]
	v_mfma_f32_16x16x32_bf16 v[110:113], v[134:137], v[190:193], v[110:113]
	v_mfma_f32_16x16x32_bf16 v[106:109], v[142:145], v[190:193], v[106:109]
	v_mfma_f32_16x16x32_bf16 v[94:97], v[134:137], v[200:203], v[94:97]
	v_mfma_f32_16x16x32_bf16 v[90:93], v[142:145], v[200:203], v[90:93]
	v_mfma_f32_16x16x32_bf16 v[78:81], v[134:137], v[214:217], v[78:81]
	v_mfma_f32_16x16x32_bf16 v[74:77], v[142:145], v[214:217], v[74:77]
	s_setprio 0
	s_setprio 1
	v_mfma_f32_16x16x32_bf16 v[118:121], v[146:149], v[172:175], v[118:121]
	v_mfma_f32_16x16x32_bf16 v[114:117], v[154:157], v[172:175], v[114:117]
	v_mfma_f32_16x16x32_bf16 v[102:105], v[146:149], v[180:183], v[102:105]
	v_mfma_f32_16x16x32_bf16 v[98:101], v[154:157], v[180:183], v[98:101]
	v_mfma_f32_16x16x32_bf16 v[86:89], v[146:149], v[196:199], v[86:89]
	v_mfma_f32_16x16x32_bf16 v[82:85], v[154:157], v[196:199], v[82:85]
	v_mfma_f32_16x16x32_bf16 v[70:73], v[146:149], v[204:207], v[70:73]
	v_mfma_f32_16x16x32_bf16 v[66:69], v[154:157], v[204:207], v[66:69]
	v_mfma_f32_16x16x32_bf16 v[118:121], v[150:153], v[176:179], v[118:121]
	v_mfma_f32_16x16x32_bf16 v[114:117], v[168:171], v[176:179], v[114:117]
	v_mfma_f32_16x16x32_bf16 v[102:105], v[150:153], v[190:193], v[102:105]
	v_mfma_f32_16x16x32_bf16 v[98:101], v[168:171], v[190:193], v[98:101]
	v_mfma_f32_16x16x32_bf16 v[86:89], v[150:153], v[200:203], v[86:89]
	v_mfma_f32_16x16x32_bf16 v[82:85], v[168:171], v[200:203], v[82:85]
	v_mfma_f32_16x16x32_bf16 v[70:73], v[150:153], v[214:217], v[70:73]
	v_mfma_f32_16x16x32_bf16 v[66:69], v[168:171], v[214:217], v[66:69]
	s_setprio 0
	s_barrier
	s_add_i32 s64, s19, s4
	v_lshl_add_u64 v[184:185], v[184:185], 0, s[12:13]
	s_mov_b32 m0, s64
	ds_read_b128 v[172:175], v189 offset:49152
	ds_read_b128 v[176:179], v189 offset:50176
	ds_read_b128 v[180:183], v189 offset:51200
	ds_read_b128 v[190:193], v189 offset:52224
	ds_read_b128 v[196:199], v189 offset:53248
	ds_read_b128 v[200:203], v189 offset:54272
	ds_read_b128 v[204:207], v189 offset:55296
	ds_read_b128 v[214:217], v189 offset:56320
	global_load_lds_dwordx4 v[184:185], off
	v_lshl_add_u64 v[184:185], v[208:209], 0, s[12:13]
	s_add_i32 m0, s64, 0x2000
	s_add_i32 s64, s69, s4
	global_load_lds_dwordx4 v[184:185], off
	v_lshl_add_u64 v[184:185], v[228:229], 0, s[12:13]
	s_mov_b32 m0, s64
	s_nop 0
	global_load_lds_dwordx4 v[184:185], off
	v_lshl_add_u64 v[184:185], v[230:231], 0, s[12:13]
	s_add_i32 m0, s64, 0x2000
	s_nop 0
	global_load_lds_dwordx4 v[184:185], off
	v_lshl_add_u64 v[184:185], v[232:233], 0, s[12:13]
	s_mov_b32 m0, s16
	s_nop 0
	global_load_lds_dwordx4 v[184:185], off
	v_lshl_add_u64 v[184:185], v[234:235], 0, s[12:13]
	s_mov_b32 m0, s17
	s_nop 0
	global_load_lds_dwordx4 v[184:185], off
	s_waitcnt vmcnt(8)
	s_waitcnt lgkmcnt(0)
	s_barrier
	s_setprio 1
	s_waitcnt lgkmcnt(0)
	v_mfma_f32_16x16x32_bf16 v[62:65], v[130:133], v[172:175], v[62:65]
	v_mfma_f32_16x16x32_bf16 v[58:61], v[138:141], v[172:175], v[58:61]
	v_mfma_f32_16x16x32_bf16 v[46:49], v[130:133], v[180:183], v[46:49]
	v_mfma_f32_16x16x32_bf16 v[42:45], v[138:141], v[180:183], v[42:45]
	v_mfma_f32_16x16x32_bf16 v[30:33], v[130:133], v[196:199], v[30:33]
	v_mfma_f32_16x16x32_bf16 v[26:29], v[138:141], v[196:199], v[26:29]
	v_mfma_f32_16x16x32_bf16 v[14:17], v[130:133], v[204:207], v[14:17]
	v_mfma_f32_16x16x32_bf16 v[10:13], v[138:141], v[204:207], v[10:13]
	v_mfma_f32_16x16x32_bf16 v[62:65], v[134:137], v[176:179], v[62:65]
	v_mfma_f32_16x16x32_bf16 v[58:61], v[142:145], v[176:179], v[58:61]
	v_mfma_f32_16x16x32_bf16 v[46:49], v[134:137], v[190:193], v[46:49]
	v_mfma_f32_16x16x32_bf16 v[42:45], v[142:145], v[190:193], v[42:45]
	v_mfma_f32_16x16x32_bf16 v[30:33], v[134:137], v[200:203], v[30:33]
	v_mfma_f32_16x16x32_bf16 v[26:29], v[142:145], v[200:203], v[26:29]
	v_mfma_f32_16x16x32_bf16 v[14:17], v[134:137], v[214:217], v[14:17]
	v_mfma_f32_16x16x32_bf16 v[10:13], v[142:145], v[214:217], v[10:13]
	s_setprio 0
	s_setprio 1
	v_mfma_f32_16x16x32_bf16 v[54:57], v[146:149], v[172:175], v[54:57]
	v_mfma_f32_16x16x32_bf16 v[50:53], v[154:157], v[172:175], v[50:53]
	v_mfma_f32_16x16x32_bf16 v[38:41], v[146:149], v[180:183], v[38:41]
	v_mfma_f32_16x16x32_bf16 v[34:37], v[154:157], v[180:183], v[34:37]
	v_mfma_f32_16x16x32_bf16 v[22:25], v[146:149], v[196:199], v[22:25]
	v_mfma_f32_16x16x32_bf16 v[18:21], v[154:157], v[196:199], v[18:21]
	v_mfma_f32_16x16x32_bf16 v[6:9], v[146:149], v[204:207], v[6:9]
	v_mfma_f32_16x16x32_bf16 v[2:5], v[154:157], v[204:207], v[2:5]
	v_mfma_f32_16x16x32_bf16 v[54:57], v[150:153], v[176:179], v[54:57]
	v_mfma_f32_16x16x32_bf16 v[50:53], v[168:171], v[176:179], v[50:53]
	v_mfma_f32_16x16x32_bf16 v[38:41], v[150:153], v[190:193], v[38:41]
	v_mfma_f32_16x16x32_bf16 v[34:37], v[168:171], v[190:193], v[34:37]
	v_mfma_f32_16x16x32_bf16 v[22:25], v[150:153], v[200:203], v[22:25]
	v_mfma_f32_16x16x32_bf16 v[18:21], v[168:171], v[200:203], v[18:21]
	v_mfma_f32_16x16x32_bf16 v[6:9], v[150:153], v[214:217], v[6:9]
	v_mfma_f32_16x16x32_bf16 v[2:5], v[168:171], v[214:217], v[2:5]
	s_setprio 0
	s_barrier
	s_add_u32 s62, s62, 0x100
	s_addc_u32 s63, s63, 0
	s_add_u32 s41, s41, 0x100
	s_addc_u32 s67, s67, 0
	s_cmp_ge_u32 s68, s23
	s_mov_b32 s64, s68
	s_cbranch_scc0 .LBB0_137
	v_lshl_or_b32 v168, s36, 8, v188
	v_lshl_add_u32 v170, s40, 8, v186
	v_ashrrev_i32_e32 v169, 31, v168
	v_cmp_lt_i32_e32 vcc, v218, v213
	v_readlane_b32 s40, v255, 36
	v_lshlrev_b64 v[198:199], 1, v[168:169]
	v_cndmask_b32_e32 v130, v211, v218, vcc
	v_cmp_lt_i32_e32 vcc, v219, v213
	v_readlane_b32 s41, v255, 37
	v_ashrrev_i32_e32 v171, 31, v170
	v_lshlrev_b32_e32 v196, 2, v130
	v_cndmask_b32_e32 v130, v211, v219, vcc
	v_lshl_add_u64 v[172:173], s[40:41], 0, v[198:199]
	v_lshlrev_b64 v[200:201], 11, v[170:171]
	v_lshlrev_b32_e32 v195, 2, v130
	v_lshl_add_u64 v[130:131], v[172:173], 0, v[200:201]
	global_load_dwordx4 v[190:193], v[130:131], off
	global_load_dwordx4 v[154:157], v[130:131], off offset:256
	v_or_b32_e32 v182, 16, v170
	v_ashrrev_i32_e32 v183, 31, v182
	v_or_b32_e32 v178, 32, v170
	v_lshlrev_b64 v[184:185], 11, v[182:183]
	v_ashrrev_i32_e32 v179, 31, v178
	v_or_b32_e32 v174, 48, v170
	v_lshl_add_u64 v[130:131], v[172:173], 0, v[184:185]
	v_lshlrev_b64 v[180:181], 11, v[178:179]
	v_ashrrev_i32_e32 v175, 31, v174
	global_load_dwordx4 v[150:153], v[130:131], off
	global_load_dwordx4 v[146:149], v[130:131], off offset:256
	v_lshl_add_u64 v[130:131], v[172:173], 0, v[180:181]
	v_lshlrev_b64 v[176:177], 11, v[174:175]
	global_load_dwordx4 v[142:145], v[130:131], off
	global_load_dwordx4 v[138:141], v[130:131], off offset:256
	v_lshl_add_u64 v[130:131], v[172:173], 0, v[176:177]
	global_load_dwordx4 v[134:137], v[130:131], off
	s_nop 0
	global_load_dwordx4 v[130:133], v[130:131], off offset:256
	s_and_b64 vcc, exec, s[58:59]
	s_cbranch_vccz .LBB0_140
	s_barrier
.LBB0_140:
	s_lshl_b32 s62, s36, 2
	s_ashr_i32 s63, s62, 31
	s_waitcnt vmcnt(0)
	v_lshlrev_b32_e32 v202, 16, v190
	v_and_b32_e32 v203, 0xffff0000, v190
	v_lshlrev_b32_e32 v190, 16, v191
	v_and_b32_e32 v191, 0xffff0000, v191
	v_lshlrev_b32_e32 v204, 16, v192
	v_and_b32_e32 v205, 0xffff0000, v192
	v_lshlrev_b32_e32 v192, 16, v193
	v_and_b32_e32 v193, 0xffff0000, v193
	v_pk_add_f32 v[128:129], v[128:129], v[190:191]
	v_pk_add_f32 v[126:127], v[126:127], v[202:203]
	v_pk_add_f32 v[190:191], v[124:125], v[192:193]
	v_mul_f32_e32 v124, v127, v127
	v_mul_f32_e32 v125, v129, v129
	v_pk_add_f32 v[122:123], v[122:123], v[204:205]
	v_fmac_f32_e32 v124, v126, v126
	v_fmac_f32_e32 v125, v128, v128
	v_add_f32_e32 v124, v124, v125
	v_mul_f32_e32 v125, v123, v123
	v_mul_f32_e32 v192, v191, v191
	v_fmac_f32_e32 v125, v122, v122
	v_fmac_f32_e32 v192, v190, v190
	v_add_f32_e32 v125, v125, v192
	v_add_f32_e32 v192, v124, v125
	v_cvt_pk_bf16_f32 v124, v126, v127
	v_cvt_pk_bf16_f32 v126, v122, v123
	v_lshl_add_u64 v[122:123], s[40:41], 0, v[200:201]
	v_cvt_pk_bf16_f32 v125, v128, v129
	v_cvt_pk_bf16_f32 v127, v190, v191
	v_lshl_add_u64 v[122:123], v[122:123], 0, v[198:199]
	global_store_dwordx4 v[122:123], v[124:127], off
	v_lshlrev_b32_e32 v128, 16, v156
	v_and_b32_e32 v129, 0xffff0000, v156
	v_lshlrev_b32_e32 v124, 16, v154
	v_and_b32_e32 v125, 0xffff0000, v154
	v_lshlrev_b32_e32 v126, 16, v155
	v_and_b32_e32 v127, 0xffff0000, v155
	v_lshlrev_b32_e32 v154, 16, v157
	v_and_b32_e32 v155, 0xffff0000, v157
	v_pk_add_f32 v[120:121], v[120:121], v[126:127]
	v_pk_add_f32 v[118:119], v[118:119], v[124:125]
	v_pk_add_f32 v[124:125], v[116:117], v[154:155]
	v_pk_add_f32 v[116:117], v[114:115], v[128:129]
	v_mul_f32_e32 v114, v119, v119
	v_mul_f32_e32 v115, v121, v121
	v_fmac_f32_e32 v114, v118, v118
	v_fmac_f32_e32 v115, v120, v120
	v_add_f32_e32 v114, v114, v115
	v_mul_f32_e32 v115, v117, v117
	v_mul_f32_e32 v126, v125, v125
	v_fmac_f32_e32 v115, v116, v116
	v_fmac_f32_e32 v126, v124, v124
	v_add_f32_e32 v115, v115, v126
	v_add_f32_e32 v114, v114, v115
	v_add_f32_e32 v126, v192, v114
	v_cvt_pk_bf16_f32 v114, v118, v119
	v_cvt_pk_bf16_f32 v115, v120, v121
	v_cvt_pk_bf16_f32 v116, v116, v117
	v_cvt_pk_bf16_f32 v117, v124, v125
	global_store_dwordx4 v[122:123], v[114:117], off offset:256
	ds_bpermute_b32 v114, v196, v126
	s_waitcnt lgkmcnt(0)
	v_add_f32_e32 v114, v126, v114
	ds_bpermute_b32 v115, v195, v114
	s_and_saveexec_b64 s[64:65], s[44:45]
	s_cbranch_execz .LBB0_142
	v_readlane_b32 s40, v255, 40
	v_lshlrev_b64 v[116:117], 6, v[170:171]
	v_readlane_b32 s41, v255, 41
	s_lshl_b32 s36, s22, 2
	s_waitcnt lgkmcnt(0)
	v_add_f32_e32 v114, v114, v115
	v_lshl_add_u64 v[116:117], s[40:41], 0, v[116:117]
	v_lshl_add_u64 v[116:117], s[62:63], 2, v[116:117]
	v_lshl_add_u64 v[116:117], v[116:117], 0, s[36:37]
	global_store_dword v[116:117], v114, off
